# RNN loop: loop-private lane mapping for y-gather/g-scatter (2-way instead of 4-way LDS bank conflicts); prep transposes issue all LDS reads of an item at once
# speedup vs baseline: 1.0171x; 1.0094x over previous
.LBB0_84:
	s_waitcnt lgkmcnt(0)
	s_barrier
	v_add_u32_e32 v0, v171, v228
	ds_read_u16 v2, v0
	ds_read_u16 v3, v0 offset:272
	v_lshlrev_b64 v[6:7], 12, v[168:169]
	v_lshl_add_u64 v[6:7], s[0:1], 0, v[6:7]
	v_mov_b32_e32 v171, v1
	v_lshl_add_u64 v[6:7], v[6:7], 0, v[170:171]
	s_waitcnt lgkmcnt(0)
	v_lshl_or_b32 v2, v3, 16, v2
	ds_read_u16 v3, v0 offset:544
	ds_read_u16 v4, v0 offset:816
	s_mov_b32 s0, 0xf80000
	v_add_co_u32_e32 v6, vcc, s0, v6
	v_readlane_b32 s0, v253, 1
	s_waitcnt lgkmcnt(0)
	v_lshl_or_b32 v3, v4, 16, v3
	ds_read_u16 v4, v0 offset:1088
	ds_read_u16 v5, v0 offset:1360
	v_addc_co_u32_e32 v7, vcc, 0, v7, vcc
	v_readlane_b32 s1, v253, 2
	s_waitcnt lgkmcnt(0)
	v_lshl_or_b32 v4, v5, 16, v4
	ds_read_u16 v5, v0 offset:1632
	ds_read_u16 v0, v0 offset:1904
	s_waitcnt lgkmcnt(0)
	v_lshl_or_b32 v5, v0, 16, v5
	global_store_dwordx4 v[6:7], v[2:5], off
	s_waitcnt lgkmcnt(0)
	s_barrier
	s_load_dword s0, s[0:1], 0x10
	s_waitcnt lgkmcnt(0)
	s_lshr_b32 s0, s0, 16
	s_cmp_lg_u32 s0, 0
	s_cselect_b64 s[0:1], -1, 0
	s_cmp_lg_u64 s[0:1], 0
	s_addc_u32 s22, s22, s94
	s_cmpk_gt_i32 s22, 0xff
	s_cbranch_scc1 .LBB0_117

.LBB0_109:
	s_or_b64 exec, exec, s[10:11]
	s_lshl_b64 s[20:21], s[0:1], 12
	s_add_u32 s0, s16, s20
	s_addc_u32 s1, s17, s21
	s_add_u32 s0, s0, s6
	s_addc_u32 s1, s1, 0
	s_add_u32 s0, s0, s7
	v_ashrrev_i32_e32 v0, 6, v182
	s_addc_u32 s1, s1, 0
	v_mov_b32_e32 v171, v1
	v_lshlrev_b32_e32 v148, 1, v168
	v_lshl_or_b32 v142, v0, 2, v213
	v_lshl_add_u64 v[146:147], s[0:1], 0, v[170:171]
	v_lshl_add_u64 v[2:3], s[26:27], 0, v[170:171]
	v_add_u32_e32 v171, s52, v148
	v_lshlrev_b32_e32 v0, 4, v0
	s_movk_i32 s6, 0x420
	v_add3_u32 v143, v213, v141, v0
	v_or_b32_e32 v220, v0, v141
	v_lshl_add_u32 v224, v141, 6, s98
	v_mul_lo_u32 v225, v142, s6
	v_mul_lo_u32 v142, v142, s51
	v_lshlrev_b32_e32 v0, 4, v141
	v_mad_u32_u24 v141, v183, s51, v171
	v_mul_lo_u32 v150, v143, s51
	v_add_u32_e32 v226, s99, v142
	v_add_u32_e32 v227, s52, v142
	ds_read_u16 v142, v141
	ds_read_u16 v151, v141 offset:272
	ds_read_u16 v143, v141 offset:544
	ds_read_u16 v153, v141 offset:816
	ds_read_u16 v144, v141 offset:1088
	ds_read_u16 v155, v141 offset:1360
	ds_read_u16 v145, v141 offset:1632
	ds_read_u16 v141, v141 offset:1904
	v_lshlrev_b64 v[184:185], 12, v[168:169]
	v_mad_u32_u24 v152, v183, s51, v252
	s_waitcnt lgkmcnt(4)
	v_perm_b32 v143, v153, v143, s8
	s_waitcnt lgkmcnt(2)
	v_perm_b32 v144, v155, v144, s8
	s_waitcnt lgkmcnt(0)
	v_perm_b32 v145, v141, v145, s8
	v_mov_b32_e32 v141, s99
	v_mad_u32_u24 v141, v183, s51, v141
	v_perm_b32 v142, v151, v142, s8
	v_lshl_add_u64 v[146:147], v[146:147], 0, v[184:185]
	v_add_u32_e32 v175, v141, v148
	global_store_dwordx4 v[146:147], v[142:145], off
	ds_write_b16 v175, v120
	ds_write_b16_d16_hi v175, v120 offset:272
	v_add_u32_e32 v120, s99, v152
	v_add_u32_e32 v200, s99, v148
	v_mad_u32_u24 v154, v183, s51, v194
	v_add_u32_e32 v141, v200, v152
	v_add_u32_e32 v201, v120, v148
	v_mad_u32_u24 v156, v183, s51, v195
	ds_write_b16 v141, v121
	ds_write_b16_d16_hi v201, v121 offset:272
	v_add_u32_e32 v120, s99, v154
	v_add_u32_e32 v121, v200, v154
	ds_write_b16 v121, v122
	v_add_u32_e32 v202, v120, v148
	v_add_u32_e32 v120, s99, v156
	v_add_u32_e32 v121, v200, v156
	v_and_b32_e32 v149, 48, v182
	ds_write_b16 v121, v123
	v_add_u32_e32 v203, v120, v148
	v_lshlrev_b64 v[120:121], 11, v[168:169]
	v_lshl_add_u64 v[120:121], v[2:3], 0, v[120:121]
	s_mov_b32 s6, 0x40000
	v_add_u32_e32 v141, 0, v149
	ds_write_b16_d16_hi v202, v122 offset:272
	ds_write_b16_d16_hi v203, v123 offset:272
	v_add_co_u32_e32 v120, vcc, s6, v120
	v_add_u32_e32 v204, 0x19c00, v141
	s_nop 0
	v_addc_co_u32_e32 v121, vcc, 0, v121, vcc
	ds_read_b128 v[142:145], v204
	global_load_dwordx4 v[120:123], v[120:121], off
	v_add_u32_e32 v205, 0, v150
	ds_read_b128 v[146:149], v204 offset:64
	ds_read_b128 v[150:153], v205
	ds_read_b128 v[154:157], v205 offset:16
	ds_read_b128 v[158:161], v205 offset:32
	ds_read_b128 v[162:165], v205 offset:48
	s_waitcnt lgkmcnt(3)
	v_mfma_f32_16x16x32_bf16 v[142:145], v[4:7], v[150:153], v[142:145]
	s_cmp_eq_u32 s28, 0
	s_cselect_b64 vcc, -1, 0
	s_cmp_eq_u32 s28, 1
	s_waitcnt lgkmcnt(1)
	v_mfma_f32_16x16x32_bf16 v[146:149], v[12:15], v[158:161], v[146:149]
	s_cselect_b64 s[40:41], -1, 0
	s_cmp_eq_u32 s28, 2
	s_cselect_b64 s[42:43], -1, 0
	v_mfma_f32_16x16x32_bf16 v[142:145], v[8:11], v[154:157], v[142:145]
	s_cmp_eq_u32 s28, 3
	s_cselect_b64 s[44:45], -1, 0
	s_add_i32 s6, 0, 0x19800
	s_waitcnt lgkmcnt(0)
	v_mfma_f32_16x16x32_bf16 v[146:149], v[16:19], v[162:165], v[146:149]
	v_add_u32_e32 v224, v224, v225
	s_nop 1
	v_cvt_pk_bf16_f32 v142, v142, v143
	v_cvt_pk_bf16_f32 v143, v144, v145
	v_cndmask_b32_e32 v167, 0, v142, vcc
	v_cndmask_b32_e32 v190, 0, v143, vcc
	s_nop 0
	v_cvt_pk_bf16_f32 v144, v146, v147
	v_cvt_pk_bf16_f32 v145, v148, v149
	v_cndmask_b32_e32 v141, 0, v144, vcc
	v_cndmask_b32_e32 v166, 0, v145, vcc
	v_mfma_f32_16x16x32_bf16 v[146:149], v[52:55], v[142:145], 0
	v_add_u32_e32 v226, v226, v0
	v_add_u32_e32 v227, v227, v0
	v_mfma_f32_16x16x32_bf16 v[150:153], v[68:71], v[142:145], 0
	v_mfma_f32_16x16x32_bf16 v[154:157], v[84:87], v[142:145], 0
	v_mfma_f32_16x16x32_bf16 v[158:161], v[100:103], v[142:145], 0
	ds_read_b128 v[142:145], v204 offset:128
	ds_read_b128 v[162:165], v205 offset:64
	ds_read_b128 v[206:209], v205 offset:80
	ds_read_b128 v[228:231], v204 offset:192
	ds_read_b128 v[238:241], v205 offset:96
	ds_read_b128 v[242:245], v205 offset:112
	s_waitcnt lgkmcnt(4)
	v_mfma_f32_16x16x32_bf16 v[142:145], v[20:23], v[162:165], v[142:145]
	s_waitcnt lgkmcnt(1)
	v_mfma_f32_16x16x32_bf16 v[162:165], v[28:31], v[238:241], v[228:231]
	v_mfma_f32_16x16x32_bf16 v[142:145], v[24:27], v[206:209], v[142:145]
	s_waitcnt lgkmcnt(0)
	v_mfma_f32_16x16x32_bf16 v[162:165], v[32:35], v[242:245], v[162:165]
	s_nop 5
	v_cvt_pk_bf16_f32 v142, v142, v143
	v_cvt_pk_bf16_f32 v143, v144, v145
	v_cvt_pk_bf16_f32 v144, v162, v163
	v_cvt_pk_bf16_f32 v145, v164, v165
	v_cndmask_b32_e64 v166, v166, v145, s[40:41]
	v_cndmask_b32_e64 v141, v141, v144, s[40:41]
	v_mfma_f32_16x16x32_bf16 v[146:149], v[56:59], v[142:145], v[146:149]
	v_cndmask_b32_e64 v190, v190, v143, s[40:41]
	v_cndmask_b32_e64 v167, v167, v142, s[40:41]
	v_mfma_f32_16x16x32_bf16 v[150:153], v[72:75], v[142:145], v[150:153]
	v_mfma_f32_16x16x32_bf16 v[154:157], v[88:91], v[142:145], v[154:157]
	v_mfma_f32_16x16x32_bf16 v[158:161], v[104:107], v[142:145], v[158:161]
	ds_read_b128 v[142:145], v204 offset:256
	ds_read_b128 v[162:165], v205 offset:128
	ds_read_b128 v[206:209], v205 offset:144
	ds_read_b128 v[228:231], v204 offset:320
	ds_read_b128 v[238:241], v205 offset:160
	ds_read_b128 v[242:245], v205 offset:176
	s_waitcnt lgkmcnt(4)
	v_mfma_f32_16x16x32_bf16 v[142:145], v[36:39], v[162:165], v[142:145]
	s_waitcnt lgkmcnt(1)
	v_mfma_f32_16x16x32_bf16 v[162:165], v[44:47], v[238:241], v[228:231]
	v_mfma_f32_16x16x32_bf16 v[142:145], v[40:43], v[206:209], v[142:145]
	v_add_u32_e32 v206, 0x21a00, v140
	v_add_u32_e32 v207, 0x22200, v140
	s_waitcnt lgkmcnt(0)
	v_mfma_f32_16x16x32_bf16 v[162:165], v[48:51], v[242:245], v[162:165]
	s_nop 3
	v_cvt_pk_bf16_f32 v142, v142, v143
	v_cvt_pk_bf16_f32 v143, v144, v145
	s_nop 1
	v_cvt_pk_bf16_f32 v144, v162, v163
	v_cvt_pk_bf16_f32 v145, v164, v165
	v_cndmask_b32_e64 v141, v141, v144, s[42:43]
	v_cndmask_b32_e64 v166, v166, v145, s[42:43]
	v_mfma_f32_16x16x32_bf16 v[146:149], v[60:63], v[142:145], v[146:149]
	v_mfma_f32_16x16x32_bf16 v[162:165], v[76:79], v[142:145], v[150:153]
	v_mfma_f32_16x16x32_bf16 v[228:231], v[92:95], v[142:145], v[154:157]
	v_mfma_f32_16x16x32_bf16 v[156:159], v[108:111], v[142:145], v[158:161]
	s_nop 2
	v_cndmask_b32_e64 v160, v167, v142, s[42:43]
	v_cndmask_b32_e64 v161, v190, v143, s[42:43]
	ds_read_b128 v[142:145], v204 offset:384
	ds_read_b128 v[150:153], v205 offset:192
	ds_read_b128 v[238:241], v205 offset:208
	ds_read_b128 v[208:211], v204 offset:448
	ds_read_b128 v[242:245], v205 offset:224
	ds_read_b128 v[246:249], v205 offset:240
	ds_read_b128 v[190:193], v206
	s_waitcnt lgkmcnt(0)
	v_mfma_f32_16x16x32_bf16 v[142:145], v[190:193], v[150:153], v[142:145]
	ds_read_b128 v[150:153], v207
	s_waitcnt lgkmcnt(0)
	v_mfma_f32_16x16x32_bf16 v[150:153], v[150:153], v[242:245], v[208:211]
	s_nop 2
	v_add_u32_e32 v208, 0x21e00, v140
	ds_read_b128 v[190:193], v208
	v_add_u32_e32 v209, 0x22600, v140
	s_waitcnt lgkmcnt(0)
	v_mfma_f32_16x16x32_bf16 v[142:145], v[190:193], v[238:241], v[142:145]
	ds_read_b128 v[190:193], v209
	s_waitcnt lgkmcnt(0)
	v_mfma_f32_16x16x32_bf16 v[150:153], v[190:193], v[246:249], v[150:153]
	s_nop 4
	v_cvt_pk_bf16_f32 v190, v142, v143
	v_cvt_pk_bf16_f32 v191, v144, v145
	s_nop 0
	v_cvt_pk_bf16_f32 v192, v150, v151
	v_cvt_pk_bf16_f32 v193, v152, v153
	v_cndmask_b32_e64 v219, v141, v192, s[44:45]
	v_cndmask_b32_e64 v218, v166, v193, s[44:45]
	v_mfma_f32_16x16x32_bf16 v[140:143], v[112:115], v[190:193], v[156:159]
	s_nop 2
	v_cndmask_b32_e64 v156, v161, v191, s[44:45]
	v_lshlrev_b32_e32 v215, 16, v156
	v_and_b32_e32 v216, 0xffff0000, v156
	v_lshlrev_b32_e32 v156, 2, v217
	v_add_u32_e32 v210, s6, v156
	v_mfma_f32_16x16x32_bf16 v[152:155], v[64:67], v[190:193], v[146:149]
	v_add_u32_e32 v211, s53, v156
	v_cndmask_b32_e64 v157, v160, v190, s[44:45]
	v_add_u32_e32 v212, s54, v156
	v_mfma_f32_16x16x32_bf16 v[144:147], v[80:83], v[190:193], v[162:165]
	v_lshlrev_b32_e32 v221, 16, v157
	v_and_b32_e32 v214, 0xffff0000, v157
	ds_read_b128 v[156:159], v212
	ds_read_b128 v[164:167], v210
	ds_read_b128 v[160:163], v211
	v_mfma_f32_16x16x32_bf16 v[148:151], v[96:99], v[190:193], v[228:231]
	s_waitcnt lgkmcnt(1)
	v_add_f32_e32 v152, v152, v164
	v_exp_f32_e32 v152, v152
	v_and_b32_e32 v164, 0xffff0000, v219
	s_waitcnt lgkmcnt(0)
	s_nop 2
	v_add_f32_e32 v148, v148, v160
	v_exp_f32_e32 v148, v148
	v_add_f32_e32 v152, 1.0, v152
	v_rcp_f32_e64 v152, -v152
	v_add_f32_e32 v149, v149, v161
	v_add_f32_e32 v148, 1.0, v148
	v_rcp_f32_e32 v148, v148
	v_mul_f32_e32 v152, v156, v152
	v_exp_f32_e32 v190, v152
	v_exp_f32_e32 v149, v149
	v_mul_f32_e32 v148, v148, v221
	v_or_b32_e32 v161, 16, v217
	v_fma_f32 v152, -v190, v190, 1.0
	v_max_f32_e32 v152, 0, v152
	v_sqrt_f32_e32 v152, v152
	v_add_f32_e32 v149, 1.0, v149
	v_rcp_f32_e32 v149, v149
	v_mul_f32_e32 v191, v148, v152
	v_mul_u32_u24_e32 v148, 0x210, v213
	v_add_lshl_u32 v160, v220, v148, 3
	v_add_f32_e32 v148, v153, v165
	v_exp_f32_e32 v148, v148
	v_mul_f32_e32 v149, v149, v214
	v_add_u32_e32 v213, s98, v160
	ds_write_b64 v213, v[190:191]
	v_add_f32_e32 v148, 1.0, v148
	v_rcp_f32_e64 v148, -v148
	v_lshlrev_b32_e32 v165, 16, v218
	v_mul_f32_e32 v148, v157, v148
	v_exp_f32_e32 v148, v148
	s_nop 0
	v_fma_f32 v152, -v148, v148, 1.0
	v_max_f32_e32 v152, 0, v152
	v_sqrt_f32_e32 v152, v152
	s_nop 0
	v_mul_f32_e32 v149, v149, v152
	v_add_u32_e32 v152, 0x420, v160
	v_add_u32_e32 v214, s98, v152
	ds_write_b64 v214, v[148:149]
	v_add_f32_e32 v148, v154, v166
	v_exp_f32_e32 v148, v148
	v_add_f32_e32 v149, v150, v162
	v_exp_f32_e32 v149, v149
	v_and_b32_e32 v166, 0xffff0000, v218
	v_add_f32_e32 v148, 1.0, v148
	v_rcp_f32_e64 v148, -v148
	v_add_f32_e32 v149, 1.0, v149
	v_rcp_f32_e32 v149, v149
	v_mul_f32_e32 v148, v158, v148
	v_exp_f32_e32 v148, v148
	v_mul_f32_e32 v149, v149, v215
	v_fma_f32 v150, -v148, v148, 1.0
	v_max_f32_e32 v150, 0, v150
	v_sqrt_f32_e32 v150, v150
	s_nop 0
	v_mul_f32_e32 v149, v149, v150
	v_add_u32_e32 v150, 0x840, v160
	v_add_u32_e32 v215, s98, v150
	ds_write_b64 v215, v[148:149]
	v_add_f32_e32 v148, v155, v167
	v_exp_f32_e32 v148, v148
	v_add_f32_e32 v149, v151, v163
	v_exp_f32_e32 v149, v149
	v_lshlrev_b32_e32 v163, 16, v219
	v_add_f32_e32 v148, 1.0, v148
	v_rcp_f32_e64 v148, -v148
	v_add_f32_e32 v149, 1.0, v149
	v_rcp_f32_e32 v149, v149
	v_mul_f32_e32 v148, v159, v148
	v_exp_f32_e32 v148, v148
	v_mul_f32_e32 v149, v149, v216
	v_fma_f32 v150, -v148, v148, 1.0
	v_max_f32_e32 v150, 0, v150
	v_sqrt_f32_e32 v150, v150
	s_nop 0
	v_mul_f32_e32 v149, v149, v150
	v_add_u32_e32 v150, 0xc60, v160
	v_add_u32_e32 v216, s98, v150
	ds_write_b64 v216, v[148:149]
	v_lshlrev_b32_e32 v148, 2, v161
	v_add_u32_e32 v217, s6, v148
	ds_read_b128 v[156:159], v217
	v_add_u32_e32 v218, s53, v148
	ds_read_b128 v[152:155], v218
	v_add_u32_e32 v219, s54, v148
	ds_read_b128 v[148:151], v219
	s_waitcnt lgkmcnt(2)
	v_add_f32_e32 v144, v144, v156
	v_exp_f32_e32 v144, v144
	s_waitcnt lgkmcnt(1)
	v_add_f32_e32 v140, v140, v152
	v_exp_f32_e32 v140, v140
	v_add_f32_e32 v141, v141, v153
	v_add_f32_e32 v144, 1.0, v144
	v_rcp_f32_e64 v144, -v144
	v_add_f32_e32 v140, 1.0, v140
	v_rcp_f32_e32 v140, v140
	v_exp_f32_e32 v141, v141
	s_waitcnt lgkmcnt(0)
	v_mul_f32_e32 v144, v148, v144
	v_exp_f32_e32 v162, v144
	v_mul_f32_e32 v140, v140, v163
	v_add_f32_e32 v141, 1.0, v141
	v_rcp_f32_e32 v141, v141
	v_fma_f32 v144, -v162, v162, 1.0
	v_max_f32_e32 v144, 0, v144
	v_sqrt_f32_e32 v144, v144
	v_mul_f32_e32 v141, v141, v164
	v_mul_f32_e32 v163, v140, v144
	v_mul_u32_u24_e32 v140, 0x84, v161
	v_add_lshl_u32 v140, v140, v220, 3
	v_add_u32_e32 v220, s98, v140
	v_add_f32_e32 v140, v145, v157
	v_exp_f32_e32 v140, v140
	ds_write_b64 v220, v[162:163]
	v_mov_b32_e32 v161, v1
	v_add_f32_e32 v140, 1.0, v140
	v_rcp_f32_e64 v140, -v140
	s_nop 0
	v_mul_f32_e32 v140, v149, v140
	v_exp_f32_e32 v140, v140
	s_nop 0
	v_fma_f32 v144, -v140, v140, 1.0
	v_max_f32_e32 v144, 0, v144
	v_sqrt_f32_e32 v144, v144
	s_nop 0
	v_mul_f32_e32 v141, v141, v144
	v_add_u32_e32 v144, 0x4620, v160
	v_add_u32_e32 v221, s98, v144
	ds_write_b64 v221, v[140:141]
	v_add_f32_e32 v140, v146, v158
	v_exp_f32_e32 v140, v140
	v_add_f32_e32 v141, v142, v154
	v_exp_f32_e32 v141, v141
	v_add_f32_e32 v140, 1.0, v140
	v_rcp_f32_e64 v140, -v140
	v_add_f32_e32 v141, 1.0, v141
	v_rcp_f32_e32 v141, v141
	v_mul_f32_e32 v140, v150, v140
	v_exp_f32_e32 v140, v140
	v_mul_f32_e32 v141, v141, v165
	v_fma_f32 v142, -v140, v140, 1.0
	v_max_f32_e32 v142, 0, v142
	v_sqrt_f32_e32 v142, v142
	s_nop 0
	v_mul_f32_e32 v141, v141, v142
	v_add_u32_e32 v142, 0x4a40, v160
	v_add_u32_e32 v222, s98, v142
	ds_write_b64 v222, v[140:141]
	v_add_f32_e32 v140, v147, v159
	v_exp_f32_e32 v140, v140
	v_add_f32_e32 v141, v143, v155
	v_exp_f32_e32 v141, v141
	v_add_f32_e32 v140, 1.0, v140
	v_rcp_f32_e64 v140, -v140
	v_add_f32_e32 v141, 1.0, v141
	v_rcp_f32_e32 v141, v141
	v_mul_f32_e32 v140, v151, v140
	v_exp_f32_e32 v140, v140
	v_mul_f32_e32 v141, v141, v166
	v_fma_f32 v142, -v140, v140, 1.0
	v_max_f32_e32 v142, 0, v142
	v_sqrt_f32_e32 v142, v142
	s_nop 0
	v_mul_f32_e32 v141, v141, v142
	v_add_u32_e32 v142, 0x4e60, v160
	v_add_u32_e32 v223, s98, v142
	ds_write_b64 v223, v[140:141]
	s_waitcnt lgkmcnt(0)
	s_barrier
	ds_read_b128 v[148:151], v224
	ds_read_b128 v[152:155], v224 offset:16
	ds_read_b128 v[144:147], v224 offset:32
	ds_read_b128 v[140:143], v224 offset:48
	s_waitcnt lgkmcnt(3)
	v_fma_f32 v149, 0, v148, v149
	v_fma_f32 v156, v150, v149, v151
	v_mul_f32_e32 v157, v148, v150
	s_waitcnt lgkmcnt(2)
	v_fma_f32 v158, v152, v156, v153
	v_mul_f32_e32 v159, v157, v152
	v_mul_f32_e32 v160, v154, v159
	v_fmac_f32_e32 v155, v154, v158
	s_waitcnt lgkmcnt(1)
	v_fma_f32 v145, v144, v155, v145
	v_mul_f32_e32 v144, v144, v160
	v_mul_f32_e32 v154, v146, v144
	v_fmac_f32_e32 v147, v146, v145
	s_waitcnt lgkmcnt(0)
	v_fma_f32 v141, v140, v147, v141
	v_mul_f32_e32 v140, v140, v154
	v_mul_f32_e32 v146, v142, v140
	v_fmac_f32_e32 v143, v142, v141
	v_mov_b32_e32 v142, 1.0
	v_mov_b32_e32 v150, v1
	v_mov_b32_e32 v151, 1.0
	v_mov_b32_dpp v142, v146 row_shr:1 row_mask:0xf bank_mask:0xf
	v_mov_b32_dpp v150, v143 row_shr:1 row_mask:0xf bank_mask:0xf
	v_fma_f32 v150, v146, v150, v143
	v_mul_f32_e32 v142, v146, v142
	v_mov_b32_e32 v152, v1
	s_nop 0
	v_mov_b32_dpp v151, v142 row_shr:2 row_mask:0xf bank_mask:0xf
	v_mov_b32_dpp v152, v150 row_shr:2 row_mask:0xf bank_mask:0xf
	v_fmac_f32_e32 v150, v142, v152
	v_mul_f32_e32 v142, v142, v151
	v_mov_b32_e32 v151, 1.0
	v_mov_b32_e32 v152, v1
	s_nop 0
	v_mov_b32_dpp v151, v142 row_shr:4 row_mask:0xf bank_mask:0xf
	v_mov_b32_dpp v152, v150 row_shr:4 row_mask:0xf bank_mask:0xf
	v_fmac_f32_e32 v150, v142, v152
	v_mul_f32_e32 v142, v142, v151
	v_mov_b32_e32 v151, 1.0
	v_mov_b32_e32 v152, v1
	s_nop 0
	v_mov_b32_dpp v151, v142 row_shr:8 row_mask:0xf bank_mask:0xf
	v_mov_b32_dpp v152, v150 row_shr:8 row_mask:0xf bank_mask:0xf
	v_fmac_f32_e32 v150, v142, v152
	v_mul_f32_e32 v142, v142, v151
	v_mov_b32_e32 v151, 1.0
	v_mov_b32_dpp v161, v150 row_shr:1 row_mask:0xf bank_mask:0xf
	v_fmac_f32_e32 v150, 0, v142
	v_mov_b32_dpp v151, v142 row_shr:1 row_mask:0xf bank_mask:0xf
	v_fmac_f32_e32 v161, 0, v151
	ds_bpermute_b32 v225, v196, v150
	ds_read_b128 v[150:153], v226
	v_fmac_f32_e32 v145, v144, v161
	v_fmac_f32_e32 v149, v148, v161
	v_fmac_f32_e32 v147, v154, v161
	v_fmac_f32_e32 v141, v140, v161
	s_waitcnt lgkmcnt(0)
	v_lshlrev_b32_e32 v163, 16, v152
	v_lshlrev_b32_e32 v142, 16, v150
	v_mul_f32_e32 v144, v145, v163
	v_mul_f32_e32 v145, 0xbfb8aa3b, v163
	v_mul_f32_e32 v148, v149, v142
	v_mul_f32_e32 v142, 0xbfb8aa3b, v142
	v_exp_f32_e32 v145, v145
	v_exp_f32_e32 v142, v142
	v_and_b32_e32 v150, 0xffff0000, v150
	v_and_b32_e32 v152, 0xffff0000, v152
	v_add_f32_e32 v145, 1.0, v145
	v_add_f32_e32 v142, 1.0, v142
	v_rcp_f32_e32 v145, v145
	v_rcp_f32_e32 v142, v142
	v_lshlrev_b32_e32 v164, 16, v153
	v_lshlrev_b32_e32 v162, 16, v151
	v_fmac_f32_e32 v156, v157, v161
	v_mul_f32_e32 v149, 0xbfb8aa3b, v150
	v_mul_f32_e32 v144, v144, v145
	v_mul_f32_e32 v145, v147, v152
	v_mul_f32_e32 v147, 0xbfb8aa3b, v152
	v_mul_f32_e32 v140, v141, v164
	v_mul_f32_e32 v141, 0xbfb8aa3b, v164
	v_mul_f32_e32 v142, v148, v142
	v_mul_f32_e32 v148, v156, v150
	v_exp_f32_e32 v149, v149
	v_mul_f32_e32 v150, 0xbfb8aa3b, v162
	v_exp_f32_e32 v147, v147
	v_exp_f32_e32 v141, v141
	v_exp_f32_e32 v150, v150
	v_add_f32_e32 v149, 1.0, v149
	v_add_f32_e32 v147, 1.0, v147
	v_add_f32_e32 v141, 1.0, v141
	v_rcp_f32_e32 v149, v149
	v_add_f32_e32 v150, 1.0, v150
	v_rcp_f32_e32 v147, v147
	v_rcp_f32_e32 v141, v141
	v_rcp_f32_e32 v150, v150
	v_and_b32_e32 v153, 0xffff0000, v153
	v_fmac_f32_e32 v158, v159, v161
	v_and_b32_e32 v151, 0xffff0000, v151
	v_mul_f32_e32 v148, v148, v149
	v_mul_f32_e32 v149, v158, v162
	v_fmac_f32_e32 v155, v160, v161
	v_mul_f32_e32 v145, v145, v147
	v_mul_f32_e32 v147, v140, v141
	v_mul_f32_e32 v141, 0xbfb8aa3b, v153
	v_mul_f32_e32 v149, v149, v150
	v_mul_f32_e32 v150, v155, v151
	v_mul_f32_e32 v151, 0xbfb8aa3b, v151
	v_exp_f32_e32 v141, v141
	v_exp_f32_e32 v151, v151
	v_fmac_f32_e32 v143, v146, v161
	v_mul_f32_e32 v140, v143, v153
	v_add_f32_e32 v141, 1.0, v141
	v_add_f32_e32 v151, 1.0, v151
	v_rcp_f32_e32 v141, v141
	v_rcp_f32_e32 v151, v151
	v_mul_f32_e32 v143, v140, v141
	v_mul_f32_e32 v150, v150, v151
	v_cvt_pk_bf16_f32 v140, v142, v148
	v_cvt_pk_bf16_f32 v141, v149, v150
	v_cvt_pk_bf16_f32 v142, v144, v145
	v_cvt_pk_bf16_f32 v143, v147, v143
	ds_write_b128 v227, v[140:143]
	s_waitcnt vmcnt(5)
	ds_write_b128 v177, v[124:127] offset:816
	s_waitcnt vmcnt(4)
	ds_write_b128 v179, v[128:131] offset:816
	s_waitcnt vmcnt(3)
	ds_write_b128 v181, v[132:135] offset:816
	s_waitcnt vmcnt(2)
	ds_write_b128 v199, v[136:139] offset:816
	s_and_saveexec_b64 s[10:11], s[38:39]
	ds_write_b128 v177, v[116:119]
	s_or_b64 exec, exec, s[10:11]
	s_lshl_b32 s7, s22, 3
	s_lshl_b32 s6, s23, 8
	s_and_b32 s7, s7, 0xc0
	s_or_b32 s6, s7, s6
	s_add_u32 s6, s6, s20
	s_addc_u32 s7, 0, s21
	v_and_b32_e32 v0, 3, v182
	v_lshl_add_u64 v[124:125], s[6:7], 0, v[184:185]
	v_lshlrev_b32_e32 v0, 4, v0
	v_lshl_add_u64 v[124:125], v[124:125], 0, v[0:1]
	v_mul_u32_u24_e32 v228, 0x110, v183
	v_lshl_add_u64 v[182:183], s[16:17], 0, v[124:125]
	s_movk_i32 s20, 0x100
	s_waitcnt vmcnt(0)
	v_readfirstlane_b32 s100, v172
	v_readfirstlane_b32 s101, v173
	v_and_b32_e32 v0, 15, v186
	v_lshlrev_b32_e32 v0, 4, v0
	v_subrev_u32_e32 v2, s100, v2
	v_lshl_add_u32 v2, v168, 11, v2
	v_lshl_or_b32 v174, v174, 11, v0
	v_lshl_or_b32 v176, v176, 11, v0
	v_lshl_or_b32 v178, v178, 11, v0
	v_lshl_or_b32 v180, v180, 11, v0
	v_and_b32_e32 v141, 63, v186
	v_and_b32_e32 v142, 15, v141
	v_lshrrev_b32_e32 v143, 4, v141
	v_lshrrev_b32_e32 v144, 6, v186
	v_lshl_or_b32 v145, v144, 4, v142
	v_mul_u32_u24_e32 v146, 0x880, v143
	v_lshl_add_u32 v146, v145, 1, v146
	v_add_u32_e32 v0, 0x1c800, v146
	v_add_u32_e32 v175, 0x1a600, v146
	v_readfirstlane_b32 s6, v2
	v_lshlrev_b32_e32 v147, 11, v142
	v_lshl_add_u32 v147, v143, 4, v147
	v_add_u32_e32 v2, s6, v147
	v_readfirstlane_b32 s6, v182
	v_readfirstlane_b32 s7, v183
	v_lshlrev_b32_e32 v148, 12, v142
	v_lshl_add_u32 v148, v143, 4, v148
	v_mov_b32_e32 v149, 0
	v_lshl_add_u64 v[182:183], s[6:7], 0, v[148:149]
	s_add_u32 s6, s100, 0x40000
	s_addc_u32 s7, s101, 0
	global_load_dwordx4 v[120:123], v2, s[6:7]
	s_waitcnt vmcnt(0)
	v_lshrrev_b32_e32 v141, 6, v186
	v_and_b32_e32 v142, 63, v186
	v_and_b32_e32 v143, 15, v142
	v_lshrrev_b32_e32 v144, 4, v142
	v_lshl_or_b32 v145, v141, 4, v143
	v_mul_u32_u24_e32 v146, 0x1100, v144
	v_lshlrev_b32_e32 v147, 3, v145
	v_lshrrev_b32_e32 v148, 1, v141
	v_lshlrev_b32_e32 v148, 4, v148
	v_add3_u32 v213, v146, v147, v148
	v_add_u32_e32 v213, 0x11000, v213
	v_lshl_add_u32 v149, v141, 2, v144
	v_mul_u32_u24_e32 v150, 0x440, v149
	v_lshlrev_b32_e32 v151, 6, v143
	v_lshrrev_b32_e32 v152, 2, v143
	v_lshlrev_b32_e32 v152, 4, v152
	v_add3_u32 v224, v150, v151, v152
	v_add_u32_e32 v224, 0x11000, v224
	s_add_u32 s100, s100, 0x80000
	s_addc_u32 s101, s101, 0
	s_sub_u32 s6, s100, 0x1800
	s_subb_u32 s7, s101, 0
	global_load_dwordx4 v[124:127], v174, s[100:101]
	global_load_dwordx4 v[128:131], v176, s[100:101]
	global_load_dwordx4 v[132:135], v178, s[100:101]
	global_load_dwordx4 v[136:139], v180, s[100:101]
	s_and_saveexec_b64 s[10:11], s[38:39]
	s_cbranch_execz .Lrnn_pre_halo
	global_load_dwordx4 v[116:119], v174, s[6:7]

.Lrnn_wd:
	ds_write_b16 v175, v120
	ds_write_b16_d16_hi v175, v120 offset:272
	ds_write_b16 v175, v121 offset:544
	ds_write_b16_d16_hi v175, v121 offset:816
	ds_write_b16 v175, v122 offset:1088
	ds_write_b16_d16_hi v175, v122 offset:1360
	ds_write_b16 v175, v123 offset:1632
	ds_write_b16_d16_hi v175, v123 offset:1904
	s_nop 0
	global_load_dwordx4 v[120:123], v2, s[100:101]
	global_store_dwordx4 v[182:183], v[148:151], off
	v_cvt_pk_bf16_f32 v140, v140, v141
	v_cvt_pk_bf16_f32 v141, v142, v143
	v_cvt_pk_bf16_f32 v142, v160, v161
	v_cvt_pk_bf16_f32 v143, v162, v163
	v_cndmask_b32_e32 v229, 0, v140, vcc
	v_cndmask_b32_e32 v230, 0, v141, vcc
	v_mfma_f32_16x16x32_bf16 v[156:159], v[52:55], v[140:143], 0
	v_cndmask_b32_e32 v184, 0, v142, vcc
	v_cndmask_b32_e32 v185, 0, v143, vcc
	v_mfma_f32_16x16x32_bf16 v[144:147], v[68:71], v[140:143], 0
	v_mfma_f32_16x16x32_bf16 v[148:151], v[84:87], v[140:143], 0
	v_mfma_f32_16x16x32_bf16 v[152:155], v[100:103], v[140:143], 0
	s_waitcnt lgkmcnt(12)
	v_mfma_f32_16x16x32_bf16 v[200:203], v[20:23], v[190:193], v[200:203]
	s_waitcnt lgkmcnt(9)
	v_mfma_f32_16x16x32_bf16 v[164:167], v[28:31], v[242:245], v[164:167]
	v_mfma_f32_16x16x32_bf16 v[200:203], v[24:27], v[238:241], v[200:203]
	s_waitcnt lgkmcnt(0)
	v_mfma_f32_16x16x32_bf16 v[164:167], v[32:35], v[246:249], v[164:167]
	ds_read_b128 v[140:143], v204 offset:256
	ds_read_b128 v[190:193], v205 offset:128
	ds_read_b128 v[238:241], v205 offset:144
	ds_read_b128 v[160:163], v204 offset:320
	ds_read_b128 v[242:245], v205 offset:160
	ds_read_b128 v[246:249], v205 offset:176
	ds_read_b128 v[214:217], v206
	ds_read_b128 v[218:221], v207
	s_nop 1
	v_cvt_pk_bf16_f32 v200, v200, v201
	v_cvt_pk_bf16_f32 v201, v202, v203
	v_cvt_pk_bf16_f32 v202, v164, v165
	v_cvt_pk_bf16_f32 v203, v166, v167
	v_cndmask_b32_e64 v229, v229, v200, s[40:41]
	v_cndmask_b32_e64 v230, v230, v201, s[40:41]
	v_mfma_f32_16x16x32_bf16 v[156:159], v[56:59], v[200:203], v[156:159]
	v_cndmask_b32_e64 v184, v184, v202, s[40:41]
	v_cndmask_b32_e64 v185, v185, v203, s[40:41]
	v_mfma_f32_16x16x32_bf16 v[144:147], v[72:75], v[200:203], v[144:147]
	v_mfma_f32_16x16x32_bf16 v[148:151], v[88:91], v[200:203], v[148:151]
	v_mfma_f32_16x16x32_bf16 v[152:155], v[104:107], v[200:203], v[152:155]
	s_waitcnt lgkmcnt(6)
	v_mfma_f32_16x16x32_bf16 v[140:143], v[36:39], v[190:193], v[140:143]
	s_waitcnt lgkmcnt(3)
	v_mfma_f32_16x16x32_bf16 v[160:163], v[44:47], v[242:245], v[160:163]
	v_mfma_f32_16x16x32_bf16 v[140:143], v[40:43], v[238:241], v[140:143]
	s_waitcnt lgkmcnt(2)
	v_mfma_f32_16x16x32_bf16 v[160:163], v[48:51], v[246:249], v[160:163]
	ds_read_b128 v[200:203], v204 offset:384
	ds_read_b128 v[190:193], v205 offset:192
	ds_read_b128 v[238:241], v205 offset:208
	ds_read_b128 v[164:167], v204 offset:448
	ds_read_b128 v[242:245], v205 offset:224
	ds_read_b128 v[246:249], v205 offset:240
	s_nop 3
	v_cvt_pk_bf16_f32 v140, v140, v141
	v_cvt_pk_bf16_f32 v141, v142, v143
	v_cvt_pk_bf16_f32 v142, v160, v161
	v_cvt_pk_bf16_f32 v143, v162, v163
	v_cndmask_b32_e64 v229, v229, v140, s[42:43]
	v_cndmask_b32_e64 v230, v230, v141, s[42:43]
	v_mfma_f32_16x16x32_bf16 v[156:159], v[60:63], v[140:143], v[156:159]
	v_cndmask_b32_e64 v184, v184, v142, s[42:43]
	v_cndmask_b32_e64 v185, v185, v143, s[42:43]
	v_mfma_f32_16x16x32_bf16 v[144:147], v[76:79], v[140:143], v[144:147]
	v_mfma_f32_16x16x32_bf16 v[148:151], v[92:95], v[140:143], v[148:151]
	v_mfma_f32_16x16x32_bf16 v[152:155], v[108:111], v[140:143], v[152:155]
	ds_read_b128 v[140:143], v208
	ds_read_b128 v[160:163], v209
	s_waitcnt lgkmcnt(6)
	v_mfma_f32_16x16x32_bf16 v[200:203], v[214:217], v[190:193], v[200:203]
	s_waitcnt lgkmcnt(3)
	v_mfma_f32_16x16x32_bf16 v[164:167], v[218:221], v[242:245], v[164:167]
	s_waitcnt lgkmcnt(1)
	v_mfma_f32_16x16x32_bf16 v[200:203], v[140:143], v[238:241], v[200:203]
	s_waitcnt lgkmcnt(0)
	v_mfma_f32_16x16x32_bf16 v[164:167], v[160:163], v[246:249], v[164:167]
	ds_read_b128 v[190:193], v210
	ds_read_b128 v[238:241], v210 offset:128
	ds_read_b128 v[242:245], v210 offset:256
	ds_read_b128 v[246:249], v210 offset:64
	ds_read_b128 v[214:217], v210 offset:192
	ds_read_b128 v[218:221], v210 offset:320
	s_nop 3
	v_cvt_pk_bf16_f32 v200, v200, v201
	v_cvt_pk_bf16_f32 v201, v202, v203
	v_cvt_pk_bf16_f32 v202, v164, v165
	v_cvt_pk_bf16_f32 v203, v166, v167
	v_cndmask_b32_e64 v229, v229, v200, s[44:45]
	v_cndmask_b32_e64 v230, v230, v201, s[44:45]
	v_mfma_f32_16x16x32_bf16 v[156:159], v[64:67], v[200:203], v[156:159]
	v_cndmask_b32_e64 v184, v184, v202, s[44:45]
	v_cndmask_b32_e64 v185, v185, v203, s[44:45]
	v_mfma_f32_16x16x32_bf16 v[144:147], v[80:83], v[200:203], v[144:147]
	v_mfma_f32_16x16x32_bf16 v[148:151], v[96:99], v[200:203], v[148:151]
	v_mfma_f32_16x16x32_bf16 v[152:155], v[112:115], v[200:203], v[152:155]
	v_lshlrev_b32_e32 v231, 16, v229
	v_and_b32_e32 v229, 0xffff0000, v229
	v_lshlrev_b32_e32 v232, 16, v230
	v_and_b32_e32 v230, 0xffff0000, v230
	v_lshlrev_b32_e32 v172, 16, v184
	v_and_b32_e32 v184, 0xffff0000, v184
	v_lshlrev_b32_e32 v3, 16, v185
	v_and_b32_e32 v185, 0xffff0000, v185
	s_nop 1
	s_waitcnt lgkmcnt(5)
	v_add_f32_e32 v156, v156, v190
	v_add_f32_e32 v157, v157, v191
	v_add_f32_e32 v158, v158, v192
	v_add_f32_e32 v159, v159, v193
	s_waitcnt lgkmcnt(4)
	v_add_f32_e32 v148, v148, v238
	v_add_f32_e32 v149, v149, v239
	v_add_f32_e32 v150, v150, v240
	v_add_f32_e32 v151, v151, v241
	v_exp_f32_e32 v156, v156
	v_exp_f32_e32 v157, v157
	v_exp_f32_e32 v158, v158
	v_exp_f32_e32 v159, v159
	v_exp_f32_e32 v148, v148
	v_exp_f32_e32 v149, v149
	v_exp_f32_e32 v150, v150
	v_exp_f32_e32 v151, v151
	s_waitcnt lgkmcnt(2)
	v_add_f32_e32 v144, v144, v246
	v_add_f32_e32 v145, v145, v247
	v_add_f32_e32 v146, v146, v248
	v_add_f32_e32 v147, v147, v249
	s_waitcnt lgkmcnt(1)
	v_add_f32_e32 v152, v152, v214
	v_add_f32_e32 v153, v153, v215
	v_add_f32_e32 v154, v154, v216
	v_add_f32_e32 v155, v155, v217
	v_exp_f32_e32 v144, v144
	v_exp_f32_e32 v145, v145
	v_exp_f32_e32 v146, v146
	v_exp_f32_e32 v147, v147
	v_exp_f32_e32 v152, v152
	v_exp_f32_e32 v153, v153
	v_exp_f32_e32 v154, v154
	v_exp_f32_e32 v155, v155
	v_add_f32_e32 v156, 1.0, v156
	v_add_f32_e32 v157, 1.0, v157
	v_add_f32_e32 v158, 1.0, v158
	v_add_f32_e32 v159, 1.0, v159
	v_add_f32_e32 v144, 1.0, v144
	v_add_f32_e32 v145, 1.0, v145
	v_add_f32_e32 v146, 1.0, v146
	v_add_f32_e32 v147, 1.0, v147
	v_add_f32_e32 v148, 1.0, v148
	v_add_f32_e32 v149, 1.0, v149
	v_add_f32_e32 v150, 1.0, v150
	v_add_f32_e32 v151, 1.0, v151
	v_add_f32_e32 v152, 1.0, v152
	v_add_f32_e32 v153, 1.0, v153
	v_add_f32_e32 v154, 1.0, v154
	v_add_f32_e32 v155, 1.0, v155
	v_rcp_f32_e64 v156, -v156
	v_rcp_f32_e64 v157, -v157
	v_rcp_f32_e64 v158, -v158
	v_rcp_f32_e64 v159, -v159
	v_rcp_f32_e64 v144, -v144
	v_rcp_f32_e64 v145, -v145
	v_rcp_f32_e64 v146, -v146
	v_rcp_f32_e64 v147, -v147
	v_rcp_f32_e32 v148, v148
	v_rcp_f32_e32 v149, v149
	v_rcp_f32_e32 v150, v150
	v_rcp_f32_e32 v151, v151
	v_rcp_f32_e32 v152, v152
	v_rcp_f32_e32 v153, v153
	v_rcp_f32_e32 v154, v154
	v_rcp_f32_e32 v155, v155
	s_waitcnt lgkmcnt(0)
	v_mul_f32_e32 v156, v242, v156
	v_mul_f32_e32 v157, v243, v157
	v_mul_f32_e32 v158, v244, v158
	v_mul_f32_e32 v159, v245, v159
	v_mul_f32_e32 v144, v218, v144
	v_mul_f32_e32 v145, v219, v145
	v_mul_f32_e32 v146, v220, v146
	v_mul_f32_e32 v147, v221, v147
	v_mul_f32_e32 v148, v148, v231
	v_mul_f32_e32 v149, v149, v229
	v_mul_f32_e32 v150, v150, v232
	v_mul_f32_e32 v151, v151, v230
	v_mul_f32_e32 v152, v152, v172
	v_mul_f32_e32 v153, v153, v184
	v_mul_f32_e32 v154, v154, v3
	v_mul_f32_e32 v155, v155, v185
	v_exp_f32_e32 v238, v156
	v_exp_f32_e32 v240, v157
	v_exp_f32_e32 v242, v158
	v_exp_f32_e32 v244, v159
	v_exp_f32_e32 v214, v144
	v_exp_f32_e32 v216, v145
	v_exp_f32_e32 v218, v146
	v_exp_f32_e32 v220, v147
	v_fma_f32 v190, -v238, v238, 1.0
	v_fma_f32 v191, -v240, v240, 1.0
	v_fma_f32 v192, -v242, v242, 1.0
	v_fma_f32 v193, -v244, v244, 1.0
	v_fma_f32 v246, -v214, v214, 1.0
	v_fma_f32 v247, -v216, v216, 1.0
	v_fma_f32 v248, -v218, v218, 1.0
	v_fma_f32 v249, -v220, v220, 1.0
	v_sqrt_f32_e32 v190, v190
	v_sqrt_f32_e32 v191, v191
	v_sqrt_f32_e32 v192, v192
	v_sqrt_f32_e32 v193, v193
	v_sqrt_f32_e32 v246, v246
	v_sqrt_f32_e32 v247, v247
	v_sqrt_f32_e32 v248, v248
	v_sqrt_f32_e32 v249, v249
	v_mul_f32_e32 v239, v148, v190
	v_mul_f32_e32 v241, v149, v191
	v_mul_f32_e32 v243, v150, v192
	v_mul_f32_e32 v245, v151, v193
	v_mul_f32_e32 v215, v152, v246
	v_mul_f32_e32 v217, v153, v247
	v_mul_f32_e32 v219, v154, v248
	v_mul_f32_e32 v221, v155, v249
	ds_write_b64 v213, v[238:239]
	ds_write_b64 v213, v[240:241] offset:1088
	ds_write_b64 v213, v[242:243] offset:2176
	ds_write_b64 v213, v[244:245] offset:3264
	ds_write_b64 v213, v[214:215] offset:17408
	ds_write_b64 v213, v[216:217] offset:18496
	ds_write_b64 v213, v[218:219] offset:19584
	ds_write_b64 v213, v[220:221] offset:20672
	v_mov_b32_e32 v161, 0
	s_waitcnt lgkmcnt(0)
	s_barrier
	ds_read_b128 v[148:151], v224
	ds_read_b128 v[152:155], v224 offset:16
	ds_read_b128 v[144:147], v224 offset:32
	ds_read_b128 v[140:143], v224 offset:48
	s_waitcnt vmcnt(2)
	ds_write_b128 v177, v[124:127] offset:816
	ds_write_b128 v179, v[128:131] offset:816
	ds_write_b128 v181, v[132:135] offset:816
	ds_write_b128 v199, v[136:139] offset:816
	s_and_saveexec_b64 s[10:11], s[38:39]
	s_cbranch_execz .Lrnn_halo_done
	ds_write_b128 v177, v[116:119]

.LBB0_161:
	v_cmp_lt_i32_e32 vcc, s61, v19
	v_lshlrev_b32_e32 v0, 2, v2
	v_add_u32_e32 v7, 0x420, v18
	v_add_u32_e32 v20, 0x428, v18
	v_add_u32_e32 v21, 0x840, v18
	v_add_u32_e32 v22, 0x848, v18
	v_add_u32_e32 v23, 0xc60, v18
	v_add_u32_e32 v24, 0xc68, v18
	v_add_u32_e32 v25, 0x1080, v18
	v_add_u32_e32 v26, 0x1088, v18
	v_add_u32_e32 v27, 0x14a0, v18
	v_add_u32_e32 v28, 0x14a8, v18
	v_add_u32_e32 v29, 0x18c0, v18
	v_add_u32_e32 v30, 0x18c8, v18
	v_add_u32_e32 v31, 0x1ce0, v18
	v_add_u32_e32 v32, 0x1ce8, v18
	v_lshlrev_b32_e32 v6, 1, v4
	s_and_saveexec_b64 s[6:7], vcc
	s_xor_b64 s[20:21], exec, s[6:7]
	s_cbranch_execz .LBB0_163
	v_add_u32_e32 v33, 0xfffff000, v19
	v_lshrrev_b32_e32 v66, 10, v33
	v_mov_b32_e32 v67, v1
	v_lshlrev_b64 v[34:35], 23, v[66:67]
	v_and_b32_e32 v68, 0x3e0, v17
	v_lshl_add_u64 v[34:35], s[84:85], 0, v[34:35]
	v_and_b32_e32 v33, 0x7c0, v16
	v_lshlrev_b32_e32 v36, 2, v68
	v_mov_b32_e32 v37, v1
	v_or_b32_e32 v38, v33, v3
	v_lshl_add_u64 v[34:35], v[34:35], 0, v[36:37]
	v_lshl_add_u64 v[34:35], v[34:35], 0, v[0:1]
	v_lshlrev_b32_e32 v0, 12, v38
	v_lshl_add_u64 v[62:63], v[34:35], 0, v[0:1]
	v_add_co_u32_e32 v38, vcc, s97, v62
	s_mov_b32 s2, 0x20000
	s_nop 0
	v_addc_co_u32_e32 v39, vcc, 0, v63, vcc
	v_add_co_u32_e32 v42, vcc, s4, v62
	global_load_dwordx4 v[34:37], v[62:63], off
	s_nop 0
	global_load_dwordx4 v[38:41], v[38:39], off
	v_addc_co_u32_e32 v43, vcc, 0, v63, vcc
	v_add_co_u32_e32 v46, vcc, s96, v62
	v_readlane_b32 s6, v253, 7
	s_nop 0
	v_addc_co_u32_e32 v47, vcc, 0, v63, vcc
	v_add_co_u32_e32 v50, vcc, s2, v62
	s_mov_b32 s2, 0x28000
	s_nop 0
	v_addc_co_u32_e32 v51, vcc, 0, v63, vcc
	v_add_co_u32_e32 v54, vcc, s2, v62
	global_load_dwordx4 v[42:45], v[42:43], off
	s_nop 0
	global_load_dwordx4 v[46:49], v[46:47], off
	v_addc_co_u32_e32 v55, vcc, 0, v63, vcc
	global_load_dwordx4 v[50:53], v[50:51], off
	s_nop 0
	global_load_dwordx4 v[54:57], v[54:55], off
	s_mov_b32 s2, 0x30000
	v_add_co_u32_e32 v58, vcc, s2, v62
	s_mov_b32 s2, 0x38000
	s_nop 0
	v_addc_co_u32_e32 v59, vcc, 0, v63, vcc
	global_load_dwordx4 v[58:61], v[58:59], off
	v_add_co_u32_e32 v62, vcc, s2, v62
	v_readlane_b32 s7, v253, 8
	s_nop 0
	v_addc_co_u32_e32 v63, vcc, 0, v63, vcc
	global_load_dwordx4 v[62:65], v[62:63], off
	v_lshlrev_b32_e32 v0, 1, v33
	s_waitcnt vmcnt(7)
	ds_write2_b32 v18, v34, v35 offset1:1
	ds_write2_b32 v18, v36, v37 offset0:2 offset1:3
	s_waitcnt vmcnt(6)
	ds_write2_b32 v7, v38, v39 offset1:1
	ds_write2_b32 v20, v40, v41 offset1:1
	s_waitcnt vmcnt(5)
	ds_write2_b32 v21, v42, v43 offset1:1
	ds_write2_b32 v22, v44, v45 offset1:1
	s_waitcnt vmcnt(4)
	ds_write2_b32 v23, v46, v47 offset1:1
	ds_write2_b32 v24, v48, v49 offset1:1
	s_waitcnt vmcnt(3)
	ds_write2_b32 v25, v50, v51 offset1:1
	ds_write2_b32 v26, v52, v53 offset1:1
	s_waitcnt vmcnt(2)
	ds_write2_b32 v27, v54, v55 offset1:1
	ds_write2_b32 v28, v56, v57 offset1:1
	s_waitcnt vmcnt(1)
	ds_write2_b32 v29, v58, v59 offset1:1
	ds_write2_b32 v30, v60, v61 offset1:1
	s_waitcnt vmcnt(0)
	ds_write2_b32 v31, v62, v63 offset1:1
	ds_write2_b32 v32, v64, v65 offset1:1
	s_waitcnt lgkmcnt(0)
	ds_read2_b32 v[108:109], v15 offset1:33
	ds_read2_b32 v[110:111], v15 offset0:66 offset1:99
	ds_read2_b32 v[112:113], v15 offset0:132 offset1:165
	ds_read2_b32 v[114:115], v15 offset0:198 offset1:231
	ds_read2_b32 v[116:117], v15 offset0:8 offset1:41
	ds_read2_b32 v[118:119], v15 offset0:74 offset1:107
	ds_read2_b32 v[120:121], v15 offset0:140 offset1:173
	ds_read2_b32 v[122:123], v15 offset0:206 offset1:239
	ds_read2_b32 v[124:125], v15 offset0:16 offset1:49
	ds_read2_b32 v[126:127], v15 offset0:82 offset1:115
	ds_read2_b32 v[128:129], v15 offset0:148 offset1:181
	ds_read2_b32 v[130:131], v15 offset0:214 offset1:247
	s_waitcnt lgkmcnt(8)
	ds_read2_b32 v[132:133], v15 offset0:24 offset1:57
	ds_read2_b32 v[134:135], v15 offset0:90 offset1:123
	ds_read2_b32 v[136:137], v15 offset0:156 offset1:189
	ds_read2_b32 v[138:139], v15 offset0:222 offset1:255
	s_waitcnt lgkmcnt(0)
	v_lshlrev_b64 v[26:27], 22, v[66:67]
	v_lshl_add_u64 v[26:27], s[6:7], 0, v[26:27]
	v_cvt_pk_bf16_f32 v20, v108, v109
	v_mov_b32_e32 v7, v1
	v_or_b32_e32 v28, v68, v3
	v_lshl_add_u64 v[26:27], v[26:27], 0, v[0:1]
	v_cvt_pk_bf16_f32 v21, v110, v111
	v_lshlrev_b32_e32 v0, 12, v28
	v_lshl_add_u64 v[6:7], v[26:27], 0, v[6:7]
	v_cvt_pk_bf16_f32 v22, v112, v113
	v_cvt_pk_bf16_f32 v23, v114, v115
	v_lshl_add_u64 v[26:27], v[6:7], 0, v[0:1]
	global_store_dwordx4 v[26:27], v[20:23], off
	v_or_b32_e32 v0, v68, v5
	v_lshlrev_b32_e32 v0, 12, v0
	v_cvt_pk_bf16_f32 v20, v116, v117
	v_cvt_pk_bf16_f32 v21, v118, v119
	v_cvt_pk_bf16_f32 v22, v120, v121
	v_cvt_pk_bf16_f32 v23, v122, v123
	v_lshl_add_u64 v[26:27], v[6:7], 0, v[0:1]
	global_store_dwordx4 v[26:27], v[20:23], off
	v_or_b32_e32 v0, v68, v10
	v_lshlrev_b32_e32 v0, 12, v0
	v_cvt_pk_bf16_f32 v20, v124, v125
	v_cvt_pk_bf16_f32 v21, v126, v127
	v_cvt_pk_bf16_f32 v22, v128, v129
	v_cvt_pk_bf16_f32 v23, v130, v131
	v_lshl_add_u64 v[26:27], v[6:7], 0, v[0:1]
	v_or_b32_e32 v0, v68, v11
	global_store_dwordx4 v[26:27], v[20:23], off
	v_lshlrev_b32_e32 v0, 12, v0
	v_lshl_add_u64 v[6:7], v[6:7], 0, v[0:1]
	v_cvt_pk_bf16_f32 v20, v132, v133
	v_cvt_pk_bf16_f32 v21, v134, v135
	v_cvt_pk_bf16_f32 v22, v136, v137
	v_cvt_pk_bf16_f32 v23, v138, v139
	global_store_dwordx4 v[6:7], v[20:23], off
	s_waitcnt lgkmcnt(0)
.LBB0_163:
	s_andn2_saveexec_b64 s[20:21], s[20:21]
	s_cbranch_execz .LBB0_160
	v_ashrrev_i32_e32 v33, 31, v19
	v_lshrrev_b32_e32 v33, 21, v33
	v_add_u32_e32 v33, v19, v33
	v_ashrrev_i32_e32 v66, 11, v33
	v_and_b32_e32 v33, 0xfffff800, v33
	v_sub_u32_e32 v33, v19, v33
	v_ashrrev_i32_e32 v36, 31, v33
	v_lshrrev_b32_e32 v36, 25, v36
	v_add_u32_e32 v36, v33, v36
	v_ashrrev_i32_e32 v37, 7, v36
	v_and_b32_e32 v36, 0x7ffff80, v36
	v_ashrrev_i32_e32 v67, 31, v66
	v_readlane_b32 s52, v253, 15
	v_sub_u32_e32 v33, v33, v36
	v_lshlrev_b32_e32 v68, 6, v37
	v_lshlrev_b64 v[34:35], 24, v[66:67]
	v_readlane_b32 s62, v253, 25
	v_readlane_b32 s63, v253, 26
	v_lshlrev_b32_e32 v70, 5, v33
	v_or_b32_e32 v62, v68, v3
	v_lshl_add_u64 v[34:35], s[62:63], 0, v[34:35]
	v_ashrrev_i32_e32 v71, 31, v70
	v_or_b32_e32 v36, 8, v62
	v_or_b32_e32 v42, 16, v62
	v_or_b32_e32 v44, 24, v62
	v_or_b32_e32 v50, 32, v62
	v_or_b32_e32 v52, 40, v62
	v_lshl_add_u64 v[34:35], v[70:71], 2, v[34:35]
	v_ashrrev_i32_e32 v63, 31, v62
	v_ashrrev_i32_e32 v37, 31, v36
	v_ashrrev_i32_e32 v43, 31, v42
	v_ashrrev_i32_e32 v45, 31, v44
	v_ashrrev_i32_e32 v51, 31, v50
	v_ashrrev_i32_e32 v53, 31, v52
	v_lshl_add_u64 v[64:65], v[34:35], 0, v[0:1]
	v_lshlrev_b64 v[34:35], 14, v[62:63]
	v_lshlrev_b64 v[36:37], 14, v[36:37]
	v_lshlrev_b64 v[42:43], 14, v[42:43]
	v_lshlrev_b64 v[44:45], 14, v[44:45]
	v_lshlrev_b64 v[50:51], 14, v[50:51]
	v_lshlrev_b64 v[52:53], 14, v[52:53]
	v_lshl_add_u64 v[34:35], v[64:65], 0, v[34:35]
	v_lshl_add_u64 v[38:39], v[64:65], 0, v[36:37]
	v_lshl_add_u64 v[42:43], v[64:65], 0, v[42:43]
	v_lshl_add_u64 v[46:47], v[64:65], 0, v[44:45]
	v_lshl_add_u64 v[50:51], v[64:65], 0, v[50:51]
	v_lshl_add_u64 v[54:55], v[64:65], 0, v[52:53]
	global_load_dwordx4 v[34:37], v[34:35], off
	s_nop 0
	global_load_dwordx4 v[38:41], v[38:39], off
	s_nop 0
	global_load_dwordx4 v[42:45], v[42:43], off
	s_nop 0
	global_load_dwordx4 v[46:49], v[46:47], off
	s_nop 0
	global_load_dwordx4 v[50:53], v[50:51], off
	s_nop 0
	global_load_dwordx4 v[54:57], v[54:55], off
	v_or_b32_e32 v58, 48, v62
	v_ashrrev_i32_e32 v59, 31, v58
	v_lshlrev_b64 v[58:59], 14, v[58:59]
	v_or_b32_e32 v62, 56, v62
	v_lshl_add_u64 v[58:59], v[64:65], 0, v[58:59]
	v_ashrrev_i32_e32 v63, 31, v62
	global_load_dwordx4 v[58:61], v[58:59], off
	v_lshlrev_b64 v[62:63], 14, v[62:63]
	v_lshl_add_u64 v[62:63], v[64:65], 0, v[62:63]
	global_load_dwordx4 v[62:65], v[62:63], off
	v_ashrrev_i32_e32 v69, 31, v68
	v_readlane_b32 s61, v253, 24
	s_movk_i32 s61, 0xfff
	v_readlane_b32 s53, v253, 16
	v_readlane_b32 s54, v253, 17
	v_readlane_b32 s55, v253, 18
	v_readlane_b32 s56, v253, 19
	v_readlane_b32 s57, v253, 20
	v_readlane_b32 s58, v253, 21
	v_readlane_b32 s59, v253, 22
	v_readlane_b32 s60, v253, 23
	v_readlane_b32 s64, v253, 27
	v_readlane_b32 s65, v253, 28
	v_readlane_b32 s66, v253, 29
	v_readlane_b32 s67, v253, 30
	s_waitcnt vmcnt(7)
	ds_write2_b32 v18, v34, v35 offset1:1
	ds_write2_b32 v18, v36, v37 offset0:2 offset1:3
	s_waitcnt vmcnt(6)
	ds_write2_b32 v7, v38, v39 offset1:1
	ds_write2_b32 v20, v40, v41 offset1:1
	s_waitcnt vmcnt(5)
	ds_write2_b32 v21, v42, v43 offset1:1
	ds_write2_b32 v22, v44, v45 offset1:1
	s_waitcnt vmcnt(4)
	ds_write2_b32 v23, v46, v47 offset1:1
	ds_write2_b32 v24, v48, v49 offset1:1
	s_waitcnt vmcnt(3)
	ds_write2_b32 v25, v50, v51 offset1:1
	ds_write2_b32 v26, v52, v53 offset1:1
	s_waitcnt vmcnt(2)
	ds_write2_b32 v27, v54, v55 offset1:1
	ds_write2_b32 v28, v56, v57 offset1:1
	s_waitcnt vmcnt(1)
	ds_write2_b32 v29, v58, v59 offset1:1
	ds_write2_b32 v30, v60, v61 offset1:1
	s_waitcnt vmcnt(0)
	ds_write2_b32 v31, v62, v63 offset1:1
	ds_write2_b32 v32, v64, v65 offset1:1
	s_waitcnt lgkmcnt(0)
	ds_read2_b32 v[108:109], v15 offset1:33
	ds_read2_b32 v[110:111], v15 offset0:66 offset1:99
	ds_read2_b32 v[112:113], v15 offset0:132 offset1:165
	ds_read2_b32 v[114:115], v15 offset0:198 offset1:231
	ds_read2_b32 v[116:117], v15 offset0:8 offset1:41
	ds_read2_b32 v[118:119], v15 offset0:74 offset1:107
	ds_read2_b32 v[120:121], v15 offset0:140 offset1:173
	ds_read2_b32 v[122:123], v15 offset0:206 offset1:239
	ds_read2_b32 v[124:125], v15 offset0:16 offset1:49
	ds_read2_b32 v[126:127], v15 offset0:82 offset1:115
	ds_read2_b32 v[128:129], v15 offset0:148 offset1:181
	ds_read2_b32 v[130:131], v15 offset0:214 offset1:247
	s_waitcnt lgkmcnt(8)
	ds_read2_b32 v[132:133], v15 offset0:24 offset1:57
	ds_read2_b32 v[134:135], v15 offset0:90 offset1:123
	ds_read2_b32 v[136:137], v15 offset0:156 offset1:189
	ds_read2_b32 v[138:139], v15 offset0:222 offset1:255
	s_waitcnt lgkmcnt(0)
	v_cvt_pk_bf16_f32 v20, v108, v109
	v_lshlrev_b64 v[24:25], 23, v[66:67]
	v_cvt_pk_bf16_f32 v21, v110, v111
	v_lshl_add_u64 v[24:25], s[90:91], 0, v[24:25]
	v_or_b32_e32 v28, v70, v3
	v_mov_b32_e32 v7, v1
	v_cvt_pk_bf16_f32 v22, v112, v113
	v_lshl_add_u64 v[24:25], v[68:69], 1, v[24:25]
	v_ashrrev_i32_e32 v29, 31, v28
	v_lshl_add_u64 v[6:7], v[24:25], 0, v[6:7]
	v_cvt_pk_bf16_f32 v23, v114, v115
	v_lshlrev_b64 v[26:27], 11, v[28:29]
	v_lshl_add_u64 v[26:27], v[6:7], 0, v[26:27]
	global_store_dwordx4 v[26:27], v[20:23], off
	v_or_b32_e32 v26, v70, v5
	v_ashrrev_i32_e32 v27, 31, v26
	v_cvt_pk_bf16_f32 v20, v116, v117
	v_lshlrev_b64 v[26:27], 11, v[26:27]
	v_cvt_pk_bf16_f32 v21, v118, v119
	v_lshl_add_u64 v[26:27], v[6:7], 0, v[26:27]
	v_cvt_pk_bf16_f32 v22, v120, v121
	v_cvt_pk_bf16_f32 v23, v122, v123
	global_store_dwordx4 v[26:27], v[20:23], off
	v_or_b32_e32 v26, v70, v10
	v_ashrrev_i32_e32 v27, 31, v26
	v_cvt_pk_bf16_f32 v20, v124, v125
	v_lshlrev_b64 v[26:27], 11, v[26:27]
	v_cvt_pk_bf16_f32 v21, v126, v127
	v_lshl_add_u64 v[26:27], v[6:7], 0, v[26:27]
	v_cvt_pk_bf16_f32 v22, v128, v129
	v_cvt_pk_bf16_f32 v23, v130, v131
	global_store_dwordx4 v[26:27], v[20:23], off
	v_or_b32_e32 v26, v70, v11
	v_ashrrev_i32_e32 v27, 31, v26
	v_cvt_pk_bf16_f32 v20, v132, v133
	v_lshlrev_b64 v[26:27], 11, v[26:27]
	v_cvt_pk_bf16_f32 v21, v134, v135
	v_lshl_add_u64 v[6:7], v[6:7], 0, v[26:27]
	v_cvt_pk_bf16_f32 v22, v136, v137
	v_cvt_pk_bf16_f32 v23, v138, v139
	global_store_dwordx4 v[6:7], v[20:23], off
	s_waitcnt lgkmcnt(0)
	s_branch .LBB0_160

.LBB0_168:
	v_add_u32_e32 v0, 0x100, v14
	s_movk_i32 s2, 0xff
	v_cmp_lt_i32_e32 vcc, s2, v0
	v_lshlrev_b32_e32 v8, 2, v2
	v_add_u32_e32 v18, 0x420, v12
	v_add_u32_e32 v19, 0x428, v12
	v_add_u32_e32 v20, 0x840, v12
	v_add_u32_e32 v21, 0x848, v12
	v_add_u32_e32 v22, 0xc60, v12
	v_add_u32_e32 v23, 0xc68, v12
	v_add_u32_e32 v24, 0x1080, v12
	v_add_u32_e32 v25, 0x1088, v12
	v_add_u32_e32 v26, 0x14a0, v12
	v_add_u32_e32 v27, 0x14a8, v12
	v_add_u32_e32 v28, 0x18c0, v12
	v_add_u32_e32 v29, 0x18c8, v12
	v_add_u32_e32 v30, 0x1ce0, v12
	v_add_u32_e32 v7, 0x1ce8, v12
	v_lshlrev_b32_e32 v6, 1, v4
	s_and_saveexec_b64 s[6:7], vcc
	s_xor_b64 s[20:21], exec, s[6:7]
	s_cbranch_execz .LBB0_170
	v_lshrrev_b32_e32 v0, 5, v14
	v_lshlrev_b64 v[32:33], 18, v[0:1]
	v_and_b32_e32 v66, 0xe0, v16
	v_lshl_add_u64 v[32:33], s[78:79], 0, v[32:33]
	v_lshlrev_b64 v[64:65], 17, v[0:1]
	v_and_b32_e32 v31, 0xc0, v15
	v_lshlrev_b32_e32 v0, 2, v66
	v_or_b32_e32 v34, v31, v3
	v_lshl_add_u64 v[32:33], v[32:33], 0, v[0:1]
	v_mov_b32_e32 v9, v1
	v_lshl_add_u64 v[8:9], v[32:33], 0, v[8:9]
	v_lshlrev_b32_e32 v0, 10, v34
	v_lshl_add_u64 v[8:9], v[8:9], 0, v[0:1]
	s_movk_i32 s2, 0x2000
	v_add_co_u32_e32 v36, vcc, s2, v8
	s_movk_i32 s2, 0x4000
	s_nop 0
	v_addc_co_u32_e32 v37, vcc, 0, v9, vcc
	v_add_co_u32_e32 v40, vcc, s2, v8
	s_mov_b32 s2, 0xa000
	s_nop 0
	v_addc_co_u32_e32 v41, vcc, 0, v9, vcc
	v_add_co_u32_e32 v44, vcc, s5, v8
	global_load_dwordx4 v[32:35], v[8:9], off
	s_nop 0
	global_load_dwordx4 v[36:39], v[36:37], off
	v_addc_co_u32_e32 v45, vcc, 0, v9, vcc
	v_add_co_u32_e32 v48, vcc, s97, v8
	global_load_dwordx4 v[40:43], v[40:41], off
	s_nop 0
	global_load_dwordx4 v[44:47], v[44:45], off
	v_addc_co_u32_e32 v49, vcc, 0, v9, vcc
	v_add_co_u32_e32 v52, vcc, s2, v8
	s_mov_b32 s2, 0xe000
	s_nop 0
	v_addc_co_u32_e32 v53, vcc, 0, v9, vcc
	global_load_dwordx4 v[48:51], v[48:49], off
	s_nop 0
	global_load_dwordx4 v[52:55], v[52:53], off
	v_add_co_u32_e32 v56, vcc, s50, v8
	v_readlane_b32 s6, v253, 11
	s_nop 0
	v_addc_co_u32_e32 v57, vcc, 0, v9, vcc
	global_load_dwordx4 v[56:59], v[56:57], off
	v_add_co_u32_e32 v8, vcc, s2, v8
	v_readlane_b32 s7, v253, 12
	s_nop 0
	v_addc_co_u32_e32 v9, vcc, 0, v9, vcc
	global_load_dwordx4 v[60:63], v[8:9], off
	v_lshlrev_b32_e32 v0, 1, v31
	s_waitcnt vmcnt(7)
	ds_write2_b32 v12, v32, v33 offset1:1
	ds_write2_b32 v12, v34, v35 offset0:2 offset1:3
	s_waitcnt vmcnt(6)
	ds_write2_b32 v18, v36, v37 offset1:1
	ds_write2_b32 v19, v38, v39 offset1:1
	s_waitcnt vmcnt(5)
	ds_write2_b32 v20, v40, v41 offset1:1
	ds_write2_b32 v21, v42, v43 offset1:1
	s_waitcnt vmcnt(4)
	ds_write2_b32 v22, v44, v45 offset1:1
	ds_write2_b32 v23, v46, v47 offset1:1
	s_waitcnt vmcnt(3)
	ds_write2_b32 v24, v48, v49 offset1:1
	ds_write2_b32 v25, v50, v51 offset1:1
	s_waitcnt vmcnt(2)
	ds_write2_b32 v26, v52, v53 offset1:1
	ds_write2_b32 v27, v54, v55 offset1:1
	s_waitcnt vmcnt(1)
	ds_write2_b32 v28, v56, v57 offset1:1
	ds_write2_b32 v29, v58, v59 offset1:1
	s_waitcnt vmcnt(0)
	ds_write2_b32 v30, v60, v61 offset1:1
	ds_write2_b32 v7, v62, v63 offset1:1
	s_waitcnt lgkmcnt(0)
	ds_read2_b32 v[108:109], v13 offset1:33
	ds_read2_b32 v[110:111], v13 offset0:66 offset1:99
	ds_read2_b32 v[112:113], v13 offset0:132 offset1:165
	ds_read2_b32 v[114:115], v13 offset0:198 offset1:231
	ds_read2_b32 v[116:117], v13 offset0:8 offset1:41
	ds_read2_b32 v[118:119], v13 offset0:74 offset1:107
	ds_read2_b32 v[120:121], v13 offset0:140 offset1:173
	ds_read2_b32 v[122:123], v13 offset0:206 offset1:239
	ds_read2_b32 v[124:125], v13 offset0:16 offset1:49
	ds_read2_b32 v[126:127], v13 offset0:82 offset1:115
	ds_read2_b32 v[128:129], v13 offset0:148 offset1:181
	ds_read2_b32 v[130:131], v13 offset0:214 offset1:247
	s_waitcnt lgkmcnt(8)
	ds_read2_b32 v[132:133], v13 offset0:24 offset1:57
	ds_read2_b32 v[134:135], v13 offset0:90 offset1:123
	ds_read2_b32 v[136:137], v13 offset0:156 offset1:189
	ds_read2_b32 v[138:139], v13 offset0:222 offset1:255
	s_waitcnt lgkmcnt(0)
	v_cvt_pk_bf16_f32 v18, v108, v109
	v_lshl_add_u64 v[22:23], s[6:7], 0, v[64:65]
	v_cvt_pk_bf16_f32 v19, v110, v111
	v_mov_b32_e32 v7, v1
	v_or_b32_e32 v24, v66, v3
	v_lshl_add_u64 v[22:23], v[22:23], 0, v[0:1]
	v_cvt_pk_bf16_f32 v20, v112, v113
	v_lshlrev_b32_e32 v0, 9, v24
	v_lshl_add_u64 v[22:23], v[22:23], 0, v[6:7]
	v_cvt_pk_bf16_f32 v21, v114, v115
	v_lshl_add_u64 v[6:7], v[22:23], 0, v[0:1]
	global_store_dwordx4 v[6:7], v[18:21], off
	v_cvt_pk_bf16_f32 v6, v116, v117
	v_or_b32_e32 v0, v66, v5
	v_cvt_pk_bf16_f32 v7, v118, v119
	v_lshlrev_b32_e32 v0, 9, v0
	v_cvt_pk_bf16_f32 v8, v120, v121
	v_cvt_pk_bf16_f32 v9, v122, v123
	v_lshl_add_u64 v[20:21], v[22:23], 0, v[0:1]
	global_store_dwordx4 v[20:21], v[6:9], off
	v_or_b32_e32 v0, v66, v10
	v_lshlrev_b32_e32 v0, 9, v0
	v_cvt_pk_bf16_f32 v6, v124, v125
	v_cvt_pk_bf16_f32 v7, v126, v127
	v_cvt_pk_bf16_f32 v8, v128, v129
	v_cvt_pk_bf16_f32 v9, v130, v131
	v_lshl_add_u64 v[20:21], v[22:23], 0, v[0:1]
	global_store_dwordx4 v[20:21], v[6:9], off
	v_or_b32_e32 v0, v66, v11
	v_lshlrev_b32_e32 v0, 9, v0
	v_cvt_pk_bf16_f32 v6, v132, v133
	v_cvt_pk_bf16_f32 v7, v134, v135
	v_cvt_pk_bf16_f32 v8, v136, v137
	v_cvt_pk_bf16_f32 v9, v138, v139
	v_lshl_add_u64 v[18:19], v[22:23], 0, v[0:1]
	global_store_dwordx4 v[18:19], v[6:9], off
	s_waitcnt lgkmcnt(0)
.LBB0_170:
	s_andn2_saveexec_b64 s[20:21], s[20:21]
	s_cbranch_execz .LBB0_167
	v_bfe_u32 v31, v0, 3, 1
	v_ashrrev_i32_e32 v32, 4, v0
	v_and_b32_e32 v66, 3, v0
	v_mov_b32_e32 v0, s73
	v_mov_b32_e32 v9, s69
	v_cmp_eq_u32_e32 vcc, 0, v31
	v_ashrrev_i32_e32 v33, 31, v32
	v_lshlrev_b64 v[64:65], 16, v[32:33]
	v_cndmask_b32_e32 v35, v0, v9, vcc
	v_mov_b32_e32 v0, s72
	v_mov_b32_e32 v9, s68
	v_cndmask_b32_e32 v34, v0, v9, vcc
	v_lshl_add_u64 v[32:33], v[34:35], 0, v[64:65]
	v_and_b32_e32 v67, 64, v17
	v_lshlrev_b32_e32 v0, 7, v66
	v_or_b32_e32 v34, v67, v3
	v_lshl_add_u64 v[32:33], v[32:33], 0, v[0:1]
	v_mov_b32_e32 v9, v1
	v_lshl_add_u64 v[8:9], v[32:33], 0, v[8:9]
	v_lshlrev_b32_e32 v0, 9, v34
	v_lshl_add_u64 v[8:9], v[8:9], 0, v[0:1]
	s_movk_i32 s2, 0x2000
	v_add_co_u32_e32 v40, vcc, s2, v8
	s_movk_i32 s2, 0x4000
	s_nop 0
	v_addc_co_u32_e32 v41, vcc, 0, v9, vcc
	v_add_co_u32_e32 v48, vcc, s2, v8
	s_movk_i32 s2, 0x7000
	s_nop 0
	v_addc_co_u32_e32 v49, vcc, 0, v9, vcc
	v_add_co_u32_e32 v56, vcc, s5, v8
	global_load_dwordx4 v[32:35], v[8:9], off
	s_nop 0
	v_addc_co_u32_e32 v57, vcc, 0, v9, vcc
	v_add_co_u32_e32 v8, vcc, s2, v8
	global_load_dwordx4 v[36:39], v[40:41], off offset:-4096
	s_nop 0
	global_load_dwordx4 v[40:43], v[40:41], off
	v_addc_co_u32_e32 v9, vcc, 0, v9, vcc
	global_load_dwordx4 v[44:47], v[48:49], off offset:-4096
	s_nop 0
	global_load_dwordx4 v[48:51], v[48:49], off
	s_nop 0
	global_load_dwordx4 v[52:55], v[56:57], off offset:-4096
	s_nop 0
	global_load_dwordx4 v[56:59], v[56:57], off
	v_readlane_b32 s6, v253, 9
	global_load_dwordx4 v[60:63], v[8:9], off
	v_readlane_b32 s7, v253, 10
	s_waitcnt vmcnt(7)
	v_mul_f32_e32 v0, 0xbfb8aa3b, v32
	v_mul_f32_e32 v8, 0xbfb8aa3b, v33
	v_mul_f32_e32 v9, 0xbfb8aa3b, v34
	v_mul_f32_e32 v32, 0xbfb8aa3b, v35
	ds_write2_b32 v12, v0, v8 offset1:1
	ds_write2_b32 v12, v9, v32 offset0:2 offset1:3
	s_waitcnt vmcnt(6)
	v_mul_f32_e32 v0, 0xbfb8aa3b, v36
	v_mul_f32_e32 v8, 0xbfb8aa3b, v37
	v_mul_f32_e32 v9, 0xbfb8aa3b, v38
	v_mul_f32_e32 v32, 0xbfb8aa3b, v39
	s_waitcnt vmcnt(5)
	v_mul_f32_e32 v33, 0xbfb8aa3b, v40
	v_mul_f32_e32 v34, 0xbfb8aa3b, v41
	v_mul_f32_e32 v35, 0xbfb8aa3b, v42
	v_mul_f32_e32 v36, 0xbfb8aa3b, v43
	s_waitcnt vmcnt(4)
	v_mul_f32_e32 v37, 0xbfb8aa3b, v44
	v_mul_f32_e32 v38, 0xbfb8aa3b, v45
	v_mul_f32_e32 v39, 0xbfb8aa3b, v46
	v_mul_f32_e32 v40, 0xbfb8aa3b, v47
	s_waitcnt vmcnt(3)
	v_mul_f32_e32 v41, 0xbfb8aa3b, v48
	v_mul_f32_e32 v42, 0xbfb8aa3b, v49
	v_mul_f32_e32 v43, 0xbfb8aa3b, v50
	v_mul_f32_e32 v44, 0xbfb8aa3b, v51
	s_waitcnt vmcnt(2)
	v_mul_f32_e32 v45, 0xbfb8aa3b, v52
	v_mul_f32_e32 v46, 0xbfb8aa3b, v53
	v_mul_f32_e32 v47, 0xbfb8aa3b, v54
	v_mul_f32_e32 v48, 0xbfb8aa3b, v55
	s_waitcnt vmcnt(1)
	v_mul_f32_e32 v49, 0xbfb8aa3b, v56
	v_mul_f32_e32 v50, 0xbfb8aa3b, v57
	v_mul_f32_e32 v51, 0xbfb8aa3b, v58
	v_mul_f32_e32 v52, 0xbfb8aa3b, v59
	s_waitcnt vmcnt(0)
	v_mul_f32_e32 v53, 0xbfb8aa3b, v60
	v_mul_f32_e32 v54, 0xbfb8aa3b, v61
	ds_write2_b32 v18, v0, v8 offset1:1
	ds_write2_b32 v19, v9, v32 offset1:1
	ds_write2_b32 v20, v33, v34 offset1:1
	ds_write2_b32 v21, v35, v36 offset1:1
	ds_write2_b32 v22, v37, v38 offset1:1
	ds_write2_b32 v23, v39, v40 offset1:1
	ds_write2_b32 v24, v41, v42 offset1:1
	ds_write2_b32 v25, v43, v44 offset1:1
	ds_write2_b32 v26, v45, v46 offset1:1
	ds_write2_b32 v27, v47, v48 offset1:1
	ds_write2_b32 v28, v49, v50 offset1:1
	ds_write2_b32 v29, v51, v52 offset1:1
	ds_write2_b32 v30, v53, v54 offset1:1
	v_mul_f32_e32 v0, 0xbfb8aa3b, v62
	v_mul_f32_e32 v8, 0xbfb8aa3b, v63
	ds_write2_b32 v7, v0, v8 offset1:1
	s_waitcnt lgkmcnt(0)
	ds_read2_b32 v[108:109], v13 offset1:33
	ds_read2_b32 v[110:111], v13 offset0:66 offset1:99
	ds_read2_b32 v[112:113], v13 offset0:132 offset1:165
	ds_read2_b32 v[114:115], v13 offset0:198 offset1:231
	ds_read2_b32 v[116:117], v13 offset0:8 offset1:41
	ds_read2_b32 v[118:119], v13 offset0:74 offset1:107
	ds_read2_b32 v[120:121], v13 offset0:140 offset1:173
	ds_read2_b32 v[122:123], v13 offset0:206 offset1:239
	ds_read2_b32 v[124:125], v13 offset0:16 offset1:49
	ds_read2_b32 v[126:127], v13 offset0:82 offset1:115
	ds_read2_b32 v[128:129], v13 offset0:148 offset1:181
	ds_read2_b32 v[130:131], v13 offset0:214 offset1:247
	s_waitcnt lgkmcnt(8)
	ds_read2_b32 v[132:133], v13 offset0:24 offset1:57
	ds_read2_b32 v[134:135], v13 offset0:90 offset1:123
	ds_read2_b32 v[136:137], v13 offset0:156 offset1:189
	ds_read2_b32 v[138:139], v13 offset0:222 offset1:255
	s_waitcnt lgkmcnt(0)
	v_lshlrev_b32_e32 v0, 6, v66
	v_cvt_pk_bf16_f32 v18, v108, v109
	v_lshl_or_b32 v24, v31, 5, v0
	v_lshl_add_u64 v[22:23], s[6:7], 0, v[64:65]
	v_lshlrev_b32_e32 v0, 1, v67
	v_cvt_pk_bf16_f32 v19, v110, v111
	v_mov_b32_e32 v7, v1
	v_or_b32_e32 v25, v24, v3
	v_lshl_add_u64 v[22:23], v[22:23], 0, v[0:1]
	v_cvt_pk_bf16_f32 v20, v112, v113
	v_lshlrev_b32_e32 v0, 8, v25
	v_lshl_add_u64 v[22:23], v[22:23], 0, v[6:7]
	v_cvt_pk_bf16_f32 v21, v114, v115
	v_lshl_add_u64 v[6:7], v[22:23], 0, v[0:1]
	global_store_dwordx4 v[6:7], v[18:21], off
	v_cvt_pk_bf16_f32 v6, v116, v117
	v_or_b32_e32 v0, v24, v5
	v_cvt_pk_bf16_f32 v7, v118, v119
	v_lshlrev_b32_e32 v0, 8, v0
	v_cvt_pk_bf16_f32 v8, v120, v121
	v_cvt_pk_bf16_f32 v9, v122, v123
	v_lshl_add_u64 v[20:21], v[22:23], 0, v[0:1]
	global_store_dwordx4 v[20:21], v[6:9], off
	v_or_b32_e32 v0, v24, v10
	v_lshlrev_b32_e32 v0, 8, v0
	v_cvt_pk_bf16_f32 v6, v124, v125
	v_cvt_pk_bf16_f32 v7, v126, v127
	v_cvt_pk_bf16_f32 v8, v128, v129
	v_cvt_pk_bf16_f32 v9, v130, v131
	v_lshl_add_u64 v[20:21], v[22:23], 0, v[0:1]
	global_store_dwordx4 v[20:21], v[6:9], off
	v_or_b32_e32 v0, v24, v11
	v_lshlrev_b32_e32 v0, 8, v0
	v_cvt_pk_bf16_f32 v6, v132, v133
	v_cvt_pk_bf16_f32 v7, v134, v135
	v_cvt_pk_bf16_f32 v8, v136, v137
	v_cvt_pk_bf16_f32 v9, v138, v139
	v_lshl_add_u64 v[18:19], v[22:23], 0, v[0:1]
	global_store_dwordx4 v[18:19], v[6:9], off
	s_waitcnt lgkmcnt(0)
	s_branch .LBB0_167
